# mixer-A loop tail trimmed: tile counters updated under the PV2 MFMAs, redundant LDS wait before the barrier removed
# speedup vs baseline: 1.0137x; 1.0035x over previous
.Lattn_dma_done_a:
	v_exp_f32_e32 v172, v128
	v_exp_f32_e32 v170, v129
	v_exp_f32_e32 v176, v130
	v_exp_f32_e32 v168, v131
	v_exp_f32_e32 v182, v132
	v_exp_f32_e32 v178, v133
	v_exp_f32_e32 v188, v134
	v_exp_f32_e32 v174, v135
	v_exp_f32_e32 v192, v136
	v_exp_f32_e32 v186, v137
	v_exp_f32_e32 v194, v138
	v_exp_f32_e32 v180, v139
	v_exp_f32_e32 v196, v140
	v_exp_f32_e32 v190, v141
	v_exp_f32_e32 v198, v142
	v_exp_f32_e32 v184, v143
	v_cvt_pk_bf16_f32 v144, v173, v169
	v_cvt_pk_bf16_f32 v145, v177, v171
	v_cvt_pk_bf16_f32 v146, v183, v175
	v_cvt_pk_bf16_f32 v147, v189, v179
	v_cvt_pk_bf16_f32 v148, v193, v181
	v_cvt_pk_bf16_f32 v149, v195, v187
	v_cvt_pk_bf16_f32 v150, v197, v185
	v_cvt_pk_bf16_f32 v151, v199, v191
	v_cvt_pk_bf16_f32 v128, v172, v170
	v_cvt_pk_bf16_f32 v129, v176, v168
	v_cvt_pk_bf16_f32 v130, v182, v178
	v_cvt_pk_bf16_f32 v131, v188, v174
	v_cvt_pk_bf16_f32 v132, v192, v186
	v_cvt_pk_bf16_f32 v133, v194, v180
	v_cvt_pk_bf16_f32 v134, v196, v190
	v_cvt_pk_bf16_f32 v135, v198, v184
	v_add3_u32 v160, s7, v162, v160
	v_xad_u32 v252, v163, 64, s7
	v_add_u32_e32 v203, s7, v203
	v_add_u32_e32 v205, s7, v206
	ds_read_b64_tr_b16 v[136:137], v160 offset:32768
	ds_read_b64_tr_b16 v[138:139], v160 offset:34816
	ds_read_b64_tr_b16 v[140:141], v160 offset:36864
	ds_read_b64_tr_b16 v[142:143], v160 offset:38912
	ds_read_b64_tr_b16 v[152:153], v252 offset:32768
	ds_read_b64_tr_b16 v[154:155], v252 offset:34816
	ds_read_b64_tr_b16 v[156:157], v252 offset:36864
	ds_read_b64_tr_b16 v[158:159], v252 offset:38912
	ds_read_b64_tr_b16 v[208:209], v203 offset:32768
	ds_read_b64_tr_b16 v[210:211], v203 offset:34816
	ds_read_b64_tr_b16 v[212:213], v203 offset:36864
	ds_read_b64_tr_b16 v[214:215], v203 offset:38912
	ds_read_b64_tr_b16 v[216:217], v205 offset:32768
	ds_read_b64_tr_b16 v[218:219], v205 offset:34816
	ds_read_b64_tr_b16 v[220:221], v205 offset:36864
	ds_read_b64_tr_b16 v[222:223], v205 offset:38912
	s_waitcnt lgkmcnt(14)
	v_mfma_f32_32x32x16_bf16 v[64:79], v[144:147], v[136:139], v[64:79]
	v_mfma_f32_32x32x16_bf16 v[0:15], v[128:131], v[136:139], v[0:15]
	s_waitcnt lgkmcnt(10)
	v_mfma_f32_32x32x16_bf16 v[80:95], v[144:147], v[152:155], v[80:95]
	v_mfma_f32_32x32x16_bf16 v[16:31], v[128:131], v[152:155], v[16:31]
	s_waitcnt lgkmcnt(6)
	v_mfma_f32_32x32x16_bf16 v[96:111], v[144:147], v[208:211], v[96:111]
	v_mfma_f32_32x32x16_bf16 v[32:47], v[128:131], v[208:211], v[32:47]
	s_waitcnt lgkmcnt(2)
	v_mfma_f32_32x32x16_bf16 v[112:127], v[144:147], v[216:219], v[112:127]
	v_mfma_f32_32x32x16_bf16 v[48:63], v[128:131], v[216:219], v[48:63]
	v_mfma_f32_32x32x16_bf16 v[64:79], v[148:151], v[140:143], v[64:79]
	v_mfma_f32_32x32x16_bf16 v[0:15], v[132:135], v[140:143], v[0:15]
	v_mfma_f32_32x32x16_bf16 v[80:95], v[148:151], v[156:159], v[80:95]
	v_mfma_f32_32x32x16_bf16 v[16:31], v[132:135], v[156:159], v[16:31]
	v_mfma_f32_32x32x16_bf16 v[96:111], v[148:151], v[212:215], v[96:111]
	v_mfma_f32_32x32x16_bf16 v[32:47], v[132:135], v[212:215], v[32:47]
	s_waitcnt lgkmcnt(0)
	v_mfma_f32_32x32x16_bf16 v[112:127], v[148:151], v[220:223], v[112:127]
	v_mfma_f32_32x32x16_bf16 v[48:63], v[132:135], v[220:223], v[48:63]
	ds_read_b128 v[128:131], v207 offset:4096
	ds_read_b128 v[132:135], v224
	ds_read_b128 v[136:139], v225 offset:4096
	ds_read_b128 v[140:143], v226
	s_waitcnt lgkmcnt(2)
	v_mfma_f32_32x32x16_bf16 v[144:159], v[128:131], v[132:135], 0
	ds_read_b128 v[128:131], v227 offset:4096
	ds_read_b128 v[132:135], v228
	s_waitcnt lgkmcnt(2)
	v_mfma_f32_32x32x16_bf16 v[144:159], v[136:139], v[140:143], v[144:159]
	ds_read_b128 v[136:139], v230 offset:4096
	ds_read_b128 v[140:143], v232
	s_waitcnt lgkmcnt(2)
	v_mfma_f32_32x32x16_bf16 v[144:159], v[128:131], v[132:135], v[144:159]
	ds_read_b128 v[128:131], v207 offset:12288
	ds_read_b128 v[132:135], v224 offset:4096
	s_waitcnt lgkmcnt(2)
	v_mfma_f32_32x32x16_bf16 v[144:159], v[136:139], v[140:143], v[144:159]
	ds_read_b128 v[208:211], v225 offset:12288
	ds_read_b128 v[212:215], v226 offset:4096
	s_waitcnt lgkmcnt(2)
	v_mfma_f32_32x32x16_bf16 v[128:143], v[128:131], v[132:135], 0
	s_nop 7
	v_exp_f32_e32 v229, v144
	v_exp_f32_e32 v145, v145
	v_exp_f32_e32 v231, v146
	v_exp_f32_e32 v147, v147
	ds_read_b128 v[216:219], v227 offset:12288
	ds_read_b128 v[220:223], v228 offset:4096
	s_waitcnt lgkmcnt(2)
	v_mfma_f32_32x32x16_bf16 v[128:143], v[208:211], v[212:215], v[128:143]
	v_exp_f32_e32 v233, v148
	v_exp_f32_e32 v235, v149
	v_exp_f32_e32 v237, v150
	v_exp_f32_e32 v239, v151
	ds_read_b128 v[148:151], v230 offset:12288
	ds_read_b128 v[208:211], v232 offset:4096
	s_waitcnt lgkmcnt(2)
	v_mfma_f32_32x32x16_bf16 v[128:143], v[216:219], v[220:223], v[128:143]
	v_exp_f32_e32 v241, v152
	v_exp_f32_e32 v243, v153
	v_exp_f32_e32 v245, v154
	v_exp_f32_e32 v247, v155
	s_waitcnt lgkmcnt(0)
	v_mfma_f32_32x32x16_bf16 v[128:143], v[148:151], v[208:211], v[128:143]
	v_exp_f32_e32 v249, v156
	v_exp_f32_e32 v251, v157
	v_exp_f32_e32 v207, v158
	v_exp_f32_e32 v163, v159
	s_nop 7
	v_exp_f32_e32 v228, v128
	v_exp_f32_e32 v146, v129
	v_exp_f32_e32 v230, v130
	v_exp_f32_e32 v144, v131
	v_exp_f32_e32 v232, v132
	v_exp_f32_e32 v238, v133
	v_exp_f32_e32 v236, v134
	v_exp_f32_e32 v234, v135
	v_exp_f32_e32 v240, v136
	v_exp_f32_e32 v246, v137
	v_exp_f32_e32 v244, v138
	v_exp_f32_e32 v242, v139
	v_exp_f32_e32 v248, v140
	v_exp_f32_e32 v162, v141
	v_exp_f32_e32 v206, v142
	v_exp_f32_e32 v250, v143
	v_cvt_pk_bf16_f32 v148, v229, v145
	v_cvt_pk_bf16_f32 v149, v231, v147
	v_cvt_pk_bf16_f32 v150, v233, v235
	v_cvt_pk_bf16_f32 v151, v237, v239
	v_cvt_pk_bf16_f32 v152, v241, v243
	v_cvt_pk_bf16_f32 v153, v245, v247
	v_cvt_pk_bf16_f32 v154, v249, v251
	v_cvt_pk_bf16_f32 v155, v207, v163
	v_cvt_pk_bf16_f32 v128, v228, v146
	v_cvt_pk_bf16_f32 v129, v230, v144
	v_cvt_pk_bf16_f32 v130, v232, v238
	v_cvt_pk_bf16_f32 v131, v236, v234
	v_cvt_pk_bf16_f32 v132, v240, v246
	v_cvt_pk_bf16_f32 v133, v244, v242
	v_cvt_pk_bf16_f32 v134, v248, v162
	v_cvt_pk_bf16_f32 v135, v206, v250
	s_addk_i32 s5, 0x4000
	s_add_i32 s4, s4, 0x10000
	s_and_b32 s7, s5, 0x4000
	ds_read_b64_tr_b16 v[136:137], v160 offset:40960
	ds_read_b64_tr_b16 v[138:139], v160 offset:43008
	ds_read_b64_tr_b16 v[140:141], v160 offset:45056
	ds_read_b64_tr_b16 v[142:143], v160 offset:47104
	ds_read_b64_tr_b16 v[156:157], v252 offset:40960
	ds_read_b64_tr_b16 v[158:159], v252 offset:43008
	ds_read_b64_tr_b16 v[208:209], v252 offset:45056
	ds_read_b64_tr_b16 v[210:211], v252 offset:47104
	ds_read_b64_tr_b16 v[212:213], v203 offset:40960
	ds_read_b64_tr_b16 v[214:215], v203 offset:43008
	ds_read_b64_tr_b16 v[216:217], v203 offset:45056
	ds_read_b64_tr_b16 v[218:219], v203 offset:47104
	ds_read_b64_tr_b16 v[220:221], v205 offset:40960
	ds_read_b64_tr_b16 v[222:223], v205 offset:43008
	ds_read_b64_tr_b16 v[224:225], v205 offset:45056
	ds_read_b64_tr_b16 v[226:227], v205 offset:47104
	s_waitcnt lgkmcnt(14)
	v_mfma_f32_32x32x16_bf16 v[64:79], v[148:151], v[136:139], v[64:79]
	v_mfma_f32_32x32x16_bf16 v[0:15], v[128:131], v[136:139], v[0:15]
	s_waitcnt lgkmcnt(10)
	v_mfma_f32_32x32x16_bf16 v[80:95], v[148:151], v[156:159], v[80:95]
	v_mfma_f32_32x32x16_bf16 v[16:31], v[128:131], v[156:159], v[16:31]
	s_waitcnt lgkmcnt(6)
	v_mfma_f32_32x32x16_bf16 v[96:111], v[148:151], v[212:215], v[96:111]
	v_mfma_f32_32x32x16_bf16 v[32:47], v[128:131], v[212:215], v[32:47]
	s_waitcnt lgkmcnt(2)
	v_mfma_f32_32x32x16_bf16 v[112:127], v[148:151], v[220:223], v[112:127]
	v_mfma_f32_32x32x16_bf16 v[48:63], v[128:131], v[220:223], v[48:63]
	v_add_f32_e64 v128, v172, v176
	v_add_f32_e64 v129, v173, v177
	v_add_f32_e64 v130, v168, v170
	v_add_f32_e64 v131, v169, v171
	v_add_f32_e64 v128, v128, 0
	v_add_f32_e64 v129, v129, 0
	v_pk_add_f32 v[136:137], v[182:183], v[188:189]
	v_pk_add_f32 v[130:131], v[130:131], 0 op_sel_hi:[1,0]
	v_pk_add_f32 v[128:129], v[136:137], v[128:129]
	v_pk_add_f32 v[136:137], v[174:175], v[178:179]
	v_pk_add_f32 v[138:139], v[232:233], v[236:237]
	v_pk_add_f32 v[130:131], v[136:137], v[130:131]
	v_pk_add_f32 v[136:137], v[192:193], v[194:195]
	v_mfma_f32_32x32x16_bf16 v[64:79], v[152:155], v[140:143], v[64:79]
	v_add_f32_e64 v128, v136, v128
	v_add_f32_e64 v129, v137, v129
	v_add_f32_e64 v136, v180, v186
	v_add_f32_e64 v137, v181, v187
	v_add_f32_e64 v130, v136, v130
	v_add_f32_e64 v131, v137, v131
	v_pk_add_f32 v[136:137], v[196:197], v[198:199]
	s_nop 0
	v_pk_add_f32 v[128:129], v[136:137], v[128:129]
	v_pk_add_f32 v[136:137], v[184:185], v[190:191]
	v_mfma_f32_32x32x16_bf16 v[0:15], v[132:135], v[140:143], v[0:15]
	v_add_f32_e64 v130, v136, v130
	v_add_f32_e64 v131, v137, v131
	v_add_f32_e64 v136, v144, v146
	v_add_f32_e64 v137, v145, v147
	v_add_f32_e64 v128, v128, v130
	v_add_f32_e64 v129, v129, v131
	v_pk_add_f32 v[130:131], v[228:229], v[230:231]
	v_pk_add_f32 v[136:137], v[136:137], 0 op_sel_hi:[1,0]
	v_pk_add_f32 v[130:131], v[130:131], 0 op_sel_hi:[1,0]
	v_pk_add_f32 v[128:129], v[166:167], v[128:129]
	v_mfma_f32_32x32x16_bf16 v[80:95], v[152:155], v[208:211], v[80:95]
	v_add_f32_e64 v130, v138, v130
	v_add_f32_e64 v131, v139, v131
	v_add_f32_e64 v138, v234, v238
	v_add_f32_e64 v139, v235, v239
	v_add_f32_e64 v136, v138, v136
	v_add_f32_e64 v137, v139, v137
	v_pk_add_f32 v[138:139], v[240:241], v[244:245]
	s_nop 0
	v_pk_add_f32 v[130:131], v[138:139], v[130:131]
	v_mfma_f32_32x32x16_bf16 v[16:31], v[132:135], v[208:211], v[16:31]
	v_add_f32_e64 v138, v242, v246
	v_add_f32_e64 v139, v243, v247
	v_add_f32_e64 v136, v138, v136
	v_add_f32_e64 v137, v139, v137
	v_add_f32_e64 v138, v248, v206
	v_add_f32_e64 v139, v249, v207
	v_pk_add_f32 v[130:131], v[138:139], v[130:131]
	v_pk_add_f32 v[138:139], v[250:251], v[162:163]
	v_mfma_f32_32x32x16_bf16 v[96:111], v[152:155], v[216:219], v[96:111]
	v_add_f32_e64 v136, v138, v136
	v_add_f32_e64 v137, v139, v137
	v_add_f32_e64 v130, v130, v136
	v_add_f32_e64 v131, v131, v137
	v_add_f32_e64 v166, v128, v130
	v_add_f32_e64 v167, v129, v131
	v_mfma_f32_32x32x16_bf16 v[32:47], v[132:135], v[216:219], v[32:47]
	s_waitcnt lgkmcnt(0)
	v_mfma_f32_32x32x16_bf16 v[112:127], v[152:155], v[224:227], v[112:127]
	v_mfma_f32_32x32x16_bf16 v[48:63], v[132:135], v[224:227], v[48:63]
	s_waitcnt vmcnt(0)
	s_cmp_eq_u32 s4, 0x400000
	s_cbranch_scc0 .Lattn_head_a
	s_barrier
